# rw_task<2> step loop unrolled x8
# baseline (speedup 1.0000x reference)
; #define LAS __attribute__((address_space(3)))
; template <int R>
; __device__ __forceinline__ void rw_task(const Params& p, LAS unsigned char* shm, const int tid, const int s, const int d, const int h, const int half) {
;     ...
;                 for (int st = 0; st < TT; ++st) {
;                     const LAS float* sb = ib + st * RW_STRIDE;
;                     f32x2 ww[4], kk[4], bb[4], kc[4], wr[4];
;                     { const f32x4 a = *(const LAS f32x4*)(sb + 8 * j), b = *(const LAS f32x4*)(sb + 8 * j + 4); ww[0] = (f32x2){a[0], a[1]}; ww[1] = (f32x2){a[2], a[3]}; ww[2] = (f32x2){b[0], b[1]}; ww[3] = (f32x2){b[2], b[3]}; }
;                     { const f32x4 a = *(const LAS f32x4*)(sb + 64 + 8 * j), b = *(const LAS f32x4*)(sb + 64 + 8 * j + 4); kk[0] = (f32x2){a[0], a[1]}; kk[1] = (f32x2){a[2], a[3]}; kk[2] = (f32x2){b[0], b[1]}; kk[3] = (f32x2){b[2], b[3]}; }
;                     { const f32x4 a = *(const LAS f32x4*)(sb + 128 + 8 * j), b = *(const LAS f32x4*)(sb + 128 + 8 * j + 4); bb[0] = (f32x2){a[0], a[1]}; bb[1] = (f32x2){a[2], a[3]}; bb[2] = (f32x2){b[0], b[1]}; bb[3] = (f32x2){b[2], b[3]}; }
;                     { const f32x4 a = *(const LAS f32x4*)(sb + 192 + 8 * j), b = *(const LAS f32x4*)(sb + 192 + 8 * j + 4); kc[0] = (f32x2){a[0], a[1]}; kc[1] = (f32x2){a[2], a[3]}; kc[2] = (f32x2){b[0], b[1]}; kc[3] = (f32x2){b[2], b[3]}; }
;                     { const f32x4 a = *(const LAS f32x4*)(sb + 256 + 8 * j), b = *(const LAS f32x4*)(sb + 256 + 8 * j + 4); wr[0] = (f32x2){a[0], a[1]}; wr[1] = (f32x2){a[2], a[3]}; wr[2] = (f32x2){b[0], b[1]}; wr[3] = (f32x2){b[2], b[3]}; }
;                     const float v0 = sb[320 + row0], v1 = R == 2 ? sb[320 + row1] : 0.f; const f32x2 sc = *(const LAS f32x2*)(sb + 384); const float br = sc[0], kr = sc[1];
;                     if constexpr (R == 2) {
;                     f32x2 pa0 = s0[0] * kk[0], px0 = s0[0] * wr[0], pa1 = s1[0] * kk[0], px1 = s1[0] * wr[0];
; #pragma unroll
;                     for (int e = 1; e < 4; ++e) { pa0 += s0[e] * kk[e]; px0 += s0[e] * wr[e]; pa1 += s1[e] * kk[e]; px1 += s1[e] * wr[e]; }
;                     const float sa0 = red8(pa0[0] + pa0[1]), x0 = red8(px0[0] + px0[1]), sa1 = red8(pa1[0] + pa1[1]), x1 = red8(px1[0] + px1[1]);
;                     const float o0 = x0 - sa0 * br + v0 * kr, o1 = x1 - sa1 * br + v1 * kr;
.Lrw2_step:
	ds_read_b128 v[74:77], v130 offset:1552
	ds_read_b128 v[78:81], v130 offset:1568
	ds_read_b128 v[82:85], v130 offset:1808
	ds_read_b128 v[86:89], v130 offset:1824
	ds_read_b128 v[92:95], v130 offset:2064
	ds_read_b128 v[96:99], v130 offset:2080
	ds_read_b128 v[100:103], v130 offset:2320
	ds_read_b128 v[104:107], v130 offset:2336
	ds_read_b128 v[108:111], v130 offset:2576
	ds_read_b128 v[112:115], v130 offset:2592
	ds_read_b32 v116, v132 offset:1552
	ds_read_b32 v117, v132 offset:1584
	ds_read_b64 v[118:119], v133 offset:3088
	s_waitcnt lgkmcnt(13)
	v_pk_mul_f32 v[120:121], v[10:11], v[36:37]
	v_pk_mul_f32 v[124:125], v[2:3], v[36:37]
	v_pk_mul_f32 v[122:123], v[10:11], v[60:61]
	v_pk_mul_f32 v[126:127], v[2:3], v[60:61]
	v_pk_fma_f32 v[120:121], v[12:13], v[38:39], v[120:121]
	v_pk_fma_f32 v[124:125], v[4:5], v[38:39], v[124:125]
	v_pk_fma_f32 v[122:123], v[12:13], v[62:63], v[122:123]
	v_pk_fma_f32 v[126:127], v[4:5], v[62:63], v[126:127]
	v_pk_fma_f32 v[120:121], v[14:15], v[40:41], v[120:121]
	v_pk_fma_f32 v[124:125], v[6:7], v[40:41], v[124:125]
	v_pk_fma_f32 v[122:123], v[14:15], v[64:65], v[122:123]
	v_pk_fma_f32 v[126:127], v[6:7], v[64:65], v[126:127]
	v_pk_fma_f32 v[120:121], v[16:17], v[42:43], v[120:121]
	v_pk_fma_f32 v[124:125], v[8:9], v[42:43], v[124:125]
	v_pk_fma_f32 v[122:123], v[16:17], v[66:67], v[122:123]
	v_pk_fma_f32 v[126:127], v[8:9], v[66:67], v[126:127]
	v_pk_mul_f32 v[136:137], v[10:11], v[28:29]
	v_pk_mul_f32 v[148:149], v[2:3], v[28:29]
	v_add_f32_e32 v120, v120, v121
	v_add_f32_e32 v124, v124, v125
	v_add_f32_e32 v122, v122, v123
	v_add_f32_e32 v126, v126, v127
	v_pk_mul_f32 v[138:139], v[12:13], v[30:31]
	v_pk_mul_f32 v[150:151], v[4:5], v[30:31]
	v_add_f32_dpp v120, v120, v120 quad_perm:[1,0,3,2] row_mask:0xf bank_mask:0xf bound_ctrl:1
	v_add_f32_dpp v124, v124, v124 quad_perm:[1,0,3,2] row_mask:0xf bank_mask:0xf bound_ctrl:1
	v_pk_mul_f32 v[140:141], v[14:15], v[32:33]
	v_pk_mul_f32 v[152:153], v[6:7], v[32:33]
	v_add_f32_dpp v122, v122, v122 quad_perm:[1,0,3,2] row_mask:0xf bank_mask:0xf bound_ctrl:1
	v_add_f32_dpp v126, v126, v126 quad_perm:[1,0,3,2] row_mask:0xf bank_mask:0xf bound_ctrl:1
	v_pk_mul_f32 v[142:143], v[16:17], v[34:35]
	v_pk_mul_f32 v[154:155], v[8:9], v[34:35]
	v_add_f32_dpp v120, v120, v120 quad_perm:[2,3,0,1] row_mask:0xf bank_mask:0xf bound_ctrl:1
	v_add_f32_dpp v124, v124, v124 quad_perm:[2,3,0,1] row_mask:0xf bank_mask:0xf bound_ctrl:1
	v_pk_fma_f32 v[136:137], v[52:53], v[68:69], v[136:137] op_sel_hi:[1,0,1]
	v_pk_fma_f32 v[148:149], v[52:53], v[68:69], v[148:149] op_sel:[0,1,0] op_sel_hi:[1,1,1]
	v_add_f32_dpp v122, v122, v122 quad_perm:[2,3,0,1] row_mask:0xf bank_mask:0xf bound_ctrl:1
	v_add_f32_dpp v126, v126, v126 quad_perm:[2,3,0,1] row_mask:0xf bank_mask:0xf bound_ctrl:1
	v_pk_fma_f32 v[138:139], v[54:55], v[68:69], v[138:139] op_sel_hi:[1,0,1]
	v_pk_fma_f32 v[150:151], v[54:55], v[68:69], v[150:151] op_sel:[0,1,0] op_sel_hi:[1,1,1]
	v_add_f32_dpp v120, v120, v120 row_half_mirror row_mask:0xf bank_mask:0xf bound_ctrl:1
	v_add_f32_dpp v124, v124, v124 row_half_mirror row_mask:0xf bank_mask:0xf bound_ctrl:1
	v_pk_fma_f32 v[140:141], v[56:57], v[68:69], v[140:141] op_sel_hi:[1,0,1]
	v_pk_fma_f32 v[152:153], v[56:57], v[68:69], v[152:153] op_sel:[0,1,0] op_sel_hi:[1,1,1]
	v_add_f32_dpp v122, v122, v122 row_half_mirror row_mask:0xf bank_mask:0xf bound_ctrl:1
	v_add_f32_dpp v126, v126, v126 row_half_mirror row_mask:0xf bank_mask:0xf bound_ctrl:1
	v_pk_fma_f32 v[142:143], v[58:59], v[68:69], v[142:143] op_sel_hi:[1,0,1]
	v_pk_fma_f32 v[154:155], v[58:59], v[68:69], v[154:155] op_sel:[0,1,0] op_sel_hi:[1,1,1]
	v_mul_f32_e32 v144, v68, v71
	v_mul_f32_e32 v145, v69, v71
	v_pk_fma_f32 v[10:11], v[44:45], v[120:121], v[136:137] op_sel_hi:[1,0,1] neg_lo:[0,1,0] neg_hi:[0,1,0]
	v_pk_fma_f32 v[2:3], v[44:45], v[124:125], v[148:149] op_sel_hi:[1,0,1] neg_lo:[0,1,0] neg_hi:[0,1,0]
	v_fma_f32 v144, -v120, v70, v144
	v_fma_f32 v145, -v124, v70, v145
	v_pk_fma_f32 v[12:13], v[46:47], v[120:121], v[138:139] op_sel_hi:[1,0,1] neg_lo:[0,1,0] neg_hi:[0,1,0]
	v_pk_fma_f32 v[4:5], v[46:47], v[124:125], v[150:151] op_sel_hi:[1,0,1] neg_lo:[0,1,0] neg_hi:[0,1,0]
	v_add_f32_e32 v128, v122, v144
	v_add_f32_e32 v129, v126, v145
	v_pk_fma_f32 v[14:15], v[48:49], v[120:121], v[140:141] op_sel_hi:[1,0,1] neg_lo:[0,1,0] neg_hi:[0,1,0]
	v_pk_fma_f32 v[6:7], v[48:49], v[124:125], v[152:153] op_sel_hi:[1,0,1] neg_lo:[0,1,0] neg_hi:[0,1,0]
	ds_write_b32 v156, v128 offset:0
	ds_write_b32 v157, v129 offset:0
	v_pk_fma_f32 v[16:17], v[50:51], v[120:121], v[142:143] op_sel_hi:[1,0,1] neg_lo:[0,1,0] neg_hi:[0,1,0]
	v_pk_fma_f32 v[8:9], v[50:51], v[124:125], v[154:155] op_sel_hi:[1,0,1] neg_lo:[0,1,0] neg_hi:[0,1,0]
	ds_read_b128 v[28:31], v130 offset:3104
	ds_read_b128 v[32:35], v130 offset:3120
	ds_read_b128 v[36:39], v130 offset:3360
	ds_read_b128 v[40:43], v130 offset:3376
	ds_read_b128 v[44:47], v130 offset:3616
	ds_read_b128 v[48:51], v130 offset:3632
	ds_read_b128 v[52:55], v130 offset:3872
	ds_read_b128 v[56:59], v130 offset:3888
	ds_read_b128 v[60:63], v130 offset:4128
	ds_read_b128 v[64:67], v130 offset:4144
	ds_read_b32 v68, v132 offset:3104
	ds_read_b32 v69, v132 offset:3136
	ds_read_b64 v[70:71], v133 offset:4640
	s_waitcnt lgkmcnt(13)
; #define LAS __attribute__((address_space(3)))
; template <int R>
; __device__ __forceinline__ void rw_task(const Params& p, LAS unsigned char* shm, const int tid, const int s, const int d, const int h, const int half) {
;     ...
;                 for (int st = 0; st < TT; ++st) {
;                     const LAS float* sb = ib + st * RW_STRIDE;
;                     f32x2 ww[4], kk[4], bb[4], kc[4], wr[4];
;                     { const f32x4 a = *(const LAS f32x4*)(sb + 8 * j), b = *(const LAS f32x4*)(sb + 8 * j + 4); ww[0] = (f32x2){a[0], a[1]}; ww[1] = (f32x2){a[2], a[3]}; ww[2] = (f32x2){b[0], b[1]}; ww[3] = (f32x2){b[2], b[3]}; }
;                     { const f32x4 a = *(const LAS f32x4*)(sb + 64 + 8 * j), b = *(const LAS f32x4*)(sb + 64 + 8 * j + 4); kk[0] = (f32x2){a[0], a[1]}; kk[1] = (f32x2){a[2], a[3]}; kk[2] = (f32x2){b[0], b[1]}; kk[3] = (f32x2){b[2], b[3]}; }
;                     { const f32x4 a = *(const LAS f32x4*)(sb + 128 + 8 * j), b = *(const LAS f32x4*)(sb + 128 + 8 * j + 4); bb[0] = (f32x2){a[0], a[1]}; bb[1] = (f32x2){a[2], a[3]}; bb[2] = (f32x2){b[0], b[1]}; bb[3] = (f32x2){b[2], b[3]}; }
;                     { const f32x4 a = *(const LAS f32x4*)(sb + 192 + 8 * j), b = *(const LAS f32x4*)(sb + 192 + 8 * j + 4); kc[0] = (f32x2){a[0], a[1]}; kc[1] = (f32x2){a[2], a[3]}; kc[2] = (f32x2){b[0], b[1]}; kc[3] = (f32x2){b[2], b[3]}; }
;                     { const f32x4 a = *(const LAS f32x4*)(sb + 256 + 8 * j), b = *(const LAS f32x4*)(sb + 256 + 8 * j + 4); wr[0] = (f32x2){a[0], a[1]}; wr[1] = (f32x2){a[2], a[3]}; wr[2] = (f32x2){b[0], b[1]}; wr[3] = (f32x2){b[2], b[3]}; }
;                     const float v0 = sb[320 + row0], v1 = R == 2 ? sb[320 + row1] : 0.f; const f32x2 sc = *(const LAS f32x2*)(sb + 384); const float br = sc[0], kr = sc[1];
;                     if constexpr (R == 2) {
;                     f32x2 pa0 = s0[0] * kk[0], px0 = s0[0] * wr[0], pa1 = s1[0] * kk[0], px1 = s1[0] * wr[0];
; #pragma unroll
;                     for (int e = 1; e < 4; ++e) { pa0 += s0[e] * kk[e]; px0 += s0[e] * wr[e]; pa1 += s1[e] * kk[e]; px1 += s1[e] * wr[e]; }
;                     const float sa0 = red8(pa0[0] + pa0[1]), x0 = red8(px0[0] + px0[1]), sa1 = red8(pa1[0] + pa1[1]), x1 = red8(px1[0] + px1[1]);
;                     const float o0 = x0 - sa0 * br + v0 * kr, o1 = x1 - sa1 * br + v1 * kr;
	v_pk_mul_f32 v[120:121], v[10:11], v[82:83]
	v_pk_mul_f32 v[124:125], v[2:3], v[82:83]
	v_pk_mul_f32 v[122:123], v[10:11], v[108:109]
	v_pk_mul_f32 v[126:127], v[2:3], v[108:109]
	v_pk_fma_f32 v[120:121], v[12:13], v[84:85], v[120:121]
	v_pk_fma_f32 v[124:125], v[4:5], v[84:85], v[124:125]
	v_pk_fma_f32 v[122:123], v[12:13], v[110:111], v[122:123]
	v_pk_fma_f32 v[126:127], v[4:5], v[110:111], v[126:127]
	v_pk_fma_f32 v[120:121], v[14:15], v[86:87], v[120:121]
	v_pk_fma_f32 v[124:125], v[6:7], v[86:87], v[124:125]
	v_pk_fma_f32 v[122:123], v[14:15], v[112:113], v[122:123]
	v_pk_fma_f32 v[126:127], v[6:7], v[112:113], v[126:127]
	v_pk_fma_f32 v[120:121], v[16:17], v[88:89], v[120:121]
	v_pk_fma_f32 v[124:125], v[8:9], v[88:89], v[124:125]
	v_pk_fma_f32 v[122:123], v[16:17], v[114:115], v[122:123]
	v_pk_fma_f32 v[126:127], v[8:9], v[114:115], v[126:127]
	v_pk_mul_f32 v[136:137], v[10:11], v[74:75]
	v_pk_mul_f32 v[148:149], v[2:3], v[74:75]
	v_add_f32_e32 v120, v120, v121
	v_add_f32_e32 v124, v124, v125
	v_add_f32_e32 v122, v122, v123
	v_add_f32_e32 v126, v126, v127
	v_pk_mul_f32 v[138:139], v[12:13], v[76:77]
	v_pk_mul_f32 v[150:151], v[4:5], v[76:77]
	v_add_f32_dpp v120, v120, v120 quad_perm:[1,0,3,2] row_mask:0xf bank_mask:0xf bound_ctrl:1
	v_add_f32_dpp v124, v124, v124 quad_perm:[1,0,3,2] row_mask:0xf bank_mask:0xf bound_ctrl:1
	v_pk_mul_f32 v[140:141], v[14:15], v[78:79]
	v_pk_mul_f32 v[152:153], v[6:7], v[78:79]
	v_add_f32_dpp v122, v122, v122 quad_perm:[1,0,3,2] row_mask:0xf bank_mask:0xf bound_ctrl:1
	v_add_f32_dpp v126, v126, v126 quad_perm:[1,0,3,2] row_mask:0xf bank_mask:0xf bound_ctrl:1
	v_pk_mul_f32 v[142:143], v[16:17], v[80:81]
	v_pk_mul_f32 v[154:155], v[8:9], v[80:81]
	v_add_f32_dpp v120, v120, v120 quad_perm:[2,3,0,1] row_mask:0xf bank_mask:0xf bound_ctrl:1
	v_add_f32_dpp v124, v124, v124 quad_perm:[2,3,0,1] row_mask:0xf bank_mask:0xf bound_ctrl:1
	v_pk_fma_f32 v[136:137], v[100:101], v[116:117], v[136:137] op_sel_hi:[1,0,1]
	v_pk_fma_f32 v[148:149], v[100:101], v[116:117], v[148:149] op_sel:[0,1,0] op_sel_hi:[1,1,1]
	v_add_f32_dpp v122, v122, v122 quad_perm:[2,3,0,1] row_mask:0xf bank_mask:0xf bound_ctrl:1
	v_add_f32_dpp v126, v126, v126 quad_perm:[2,3,0,1] row_mask:0xf bank_mask:0xf bound_ctrl:1
	v_pk_fma_f32 v[138:139], v[102:103], v[116:117], v[138:139] op_sel_hi:[1,0,1]
	v_pk_fma_f32 v[150:151], v[102:103], v[116:117], v[150:151] op_sel:[0,1,0] op_sel_hi:[1,1,1]
	v_add_f32_dpp v120, v120, v120 row_half_mirror row_mask:0xf bank_mask:0xf bound_ctrl:1
	v_add_f32_dpp v124, v124, v124 row_half_mirror row_mask:0xf bank_mask:0xf bound_ctrl:1
	v_pk_fma_f32 v[140:141], v[104:105], v[116:117], v[140:141] op_sel_hi:[1,0,1]
	v_pk_fma_f32 v[152:153], v[104:105], v[116:117], v[152:153] op_sel:[0,1,0] op_sel_hi:[1,1,1]
	v_add_f32_dpp v122, v122, v122 row_half_mirror row_mask:0xf bank_mask:0xf bound_ctrl:1
	v_add_f32_dpp v126, v126, v126 row_half_mirror row_mask:0xf bank_mask:0xf bound_ctrl:1
	v_pk_fma_f32 v[142:143], v[106:107], v[116:117], v[142:143] op_sel_hi:[1,0,1]
	v_pk_fma_f32 v[154:155], v[106:107], v[116:117], v[154:155] op_sel:[0,1,0] op_sel_hi:[1,1,1]
	v_mul_f32_e32 v144, v116, v119
	v_mul_f32_e32 v145, v117, v119
	v_pk_fma_f32 v[10:11], v[92:93], v[120:121], v[136:137] op_sel_hi:[1,0,1] neg_lo:[0,1,0] neg_hi:[0,1,0]
	v_pk_fma_f32 v[2:3], v[92:93], v[124:125], v[148:149] op_sel_hi:[1,0,1] neg_lo:[0,1,0] neg_hi:[0,1,0]
	v_fma_f32 v144, -v120, v118, v144
	v_fma_f32 v145, -v124, v118, v145
	v_pk_fma_f32 v[12:13], v[94:95], v[120:121], v[138:139] op_sel_hi:[1,0,1] neg_lo:[0,1,0] neg_hi:[0,1,0]
	v_pk_fma_f32 v[4:5], v[94:95], v[124:125], v[150:151] op_sel_hi:[1,0,1] neg_lo:[0,1,0] neg_hi:[0,1,0]
	v_add_f32_e32 v128, v122, v144
	v_add_f32_e32 v129, v126, v145
	v_pk_fma_f32 v[14:15], v[96:97], v[120:121], v[140:141] op_sel_hi:[1,0,1] neg_lo:[0,1,0] neg_hi:[0,1,0]
	v_pk_fma_f32 v[6:7], v[96:97], v[124:125], v[152:153] op_sel_hi:[1,0,1] neg_lo:[0,1,0] neg_hi:[0,1,0]
	ds_write_b32 v156, v128 offset:256
	ds_write_b32 v157, v129 offset:256
	v_pk_fma_f32 v[16:17], v[98:99], v[120:121], v[142:143] op_sel_hi:[1,0,1] neg_lo:[0,1,0] neg_hi:[0,1,0]
	v_pk_fma_f32 v[8:9], v[98:99], v[124:125], v[154:155] op_sel_hi:[1,0,1] neg_lo:[0,1,0] neg_hi:[0,1,0]
	ds_read_b128 v[74:77], v130 offset:4656
	ds_read_b128 v[78:81], v130 offset:4672
	ds_read_b128 v[82:85], v130 offset:4912
	ds_read_b128 v[86:89], v130 offset:4928
	ds_read_b128 v[92:95], v130 offset:5168
	ds_read_b128 v[96:99], v130 offset:5184
	ds_read_b128 v[100:103], v130 offset:5424
	ds_read_b128 v[104:107], v130 offset:5440
	ds_read_b128 v[108:111], v130 offset:5680
	ds_read_b128 v[112:115], v130 offset:5696
	ds_read_b32 v116, v132 offset:4656
	ds_read_b32 v117, v132 offset:4688
	ds_read_b64 v[118:119], v133 offset:6192
	s_waitcnt lgkmcnt(13)
; #define LAS __attribute__((address_space(3)))
; template <int R>
; __device__ __forceinline__ void rw_task(const Params& p, LAS unsigned char* shm, const int tid, const int s, const int d, const int h, const int half) {
;     ...
;                     { const f32x4 a = *(const LAS f32x4*)(sb + 8 * j), b = *(const LAS f32x4*)(sb + 8 * j + 4); ww[0] = (f32x2){a[0], a[1]}; ww[1] = (f32x2){a[2], a[3]}; ww[2] = (f32x2){b[0], b[1]}; ww[3] = (f32x2){b[2], b[3]}; }
;                     { const f32x4 a = *(const LAS f32x4*)(sb + 64 + 8 * j), b = *(const LAS f32x4*)(sb + 64 + 8 * j + 4); kk[0] = (f32x2){a[0], a[1]}; kk[1] = (f32x2){a[2], a[3]}; kk[2] = (f32x2){b[0], b[1]}; kk[3] = (f32x2){b[2], b[3]}; }
;                     { const f32x4 a = *(const LAS f32x4*)(sb + 128 + 8 * j), b = *(const LAS f32x4*)(sb + 128 + 8 * j + 4); bb[0] = (f32x2){a[0], a[1]}; bb[1] = (f32x2){a[2], a[3]}; bb[2] = (f32x2){b[0], b[1]}; bb[3] = (f32x2){b[2], b[3]}; }
;                     { const f32x4 a = *(const LAS f32x4*)(sb + 192 + 8 * j), b = *(const LAS f32x4*)(sb + 192 + 8 * j + 4); kc[0] = (f32x2){a[0], a[1]}; kc[1] = (f32x2){a[2], a[3]}; kc[2] = (f32x2){b[0], b[1]}; kc[3] = (f32x2){b[2], b[3]}; }
;                     { const f32x4 a = *(const LAS f32x4*)(sb + 256 + 8 * j), b = *(const LAS f32x4*)(sb + 256 + 8 * j + 4); wr[0] = (f32x2){a[0], a[1]}; wr[1] = (f32x2){a[2], a[3]}; wr[2] = (f32x2){b[0], b[1]}; wr[3] = (f32x2){b[2], b[3]}; }
;                     const float v0 = sb[320 + row0], v1 = R == 2 ? sb[320 + row1] : 0.f; const f32x2 sc = *(const LAS f32x2*)(sb + 384); const float br = sc[0], kr = sc[1];
;                     if constexpr (R == 2) {
;                     f32x2 pa0 = s0[0] * kk[0], px0 = s0[0] * wr[0], pa1 = s1[0] * kk[0], px1 = s1[0] * wr[0];
; #pragma unroll
;                     for (int e = 1; e < 4; ++e) { pa0 += s0[e] * kk[e]; px0 += s0[e] * wr[e]; pa1 += s1[e] * kk[e]; px1 += s1[e] * wr[e]; }
;                     const float sa0 = red8(pa0[0] + pa0[1]), x0 = red8(px0[0] + px0[1]), sa1 = red8(pa1[0] + pa1[1]), x1 = red8(px1[0] + px1[1]);
;                     const float o0 = x0 - sa0 * br + v0 * kr, o1 = x1 - sa1 * br + v1 * kr;
;                     const f32x2 nsa0 = (f32x2){-sa0, -sa0}, nsa1 = (f32x2){-sa1, -sa1}, vv0 = (f32x2){v0, v0}, vv1 = (f32x2){v1, v1};
; #pragma unroll
	v_pk_mul_f32 v[120:121], v[10:11], v[36:37]
	v_pk_mul_f32 v[124:125], v[2:3], v[36:37]
	v_pk_mul_f32 v[122:123], v[10:11], v[60:61]
	v_pk_mul_f32 v[126:127], v[2:3], v[60:61]
	v_pk_fma_f32 v[120:121], v[12:13], v[38:39], v[120:121]
	v_pk_fma_f32 v[124:125], v[4:5], v[38:39], v[124:125]
	v_pk_fma_f32 v[122:123], v[12:13], v[62:63], v[122:123]
	v_pk_fma_f32 v[126:127], v[4:5], v[62:63], v[126:127]
	v_pk_fma_f32 v[120:121], v[14:15], v[40:41], v[120:121]
	v_pk_fma_f32 v[124:125], v[6:7], v[40:41], v[124:125]
	v_pk_fma_f32 v[122:123], v[14:15], v[64:65], v[122:123]
	v_pk_fma_f32 v[126:127], v[6:7], v[64:65], v[126:127]
	v_pk_fma_f32 v[120:121], v[16:17], v[42:43], v[120:121]
	v_pk_fma_f32 v[124:125], v[8:9], v[42:43], v[124:125]
	v_pk_fma_f32 v[122:123], v[16:17], v[66:67], v[122:123]
	v_pk_fma_f32 v[126:127], v[8:9], v[66:67], v[126:127]
	v_pk_mul_f32 v[136:137], v[10:11], v[28:29]
	v_pk_mul_f32 v[148:149], v[2:3], v[28:29]
	v_add_f32_e32 v120, v120, v121
	v_add_f32_e32 v124, v124, v125
	v_add_f32_e32 v122, v122, v123
	v_add_f32_e32 v126, v126, v127
	v_pk_mul_f32 v[138:139], v[12:13], v[30:31]
	v_pk_mul_f32 v[150:151], v[4:5], v[30:31]
	v_add_f32_dpp v120, v120, v120 quad_perm:[1,0,3,2] row_mask:0xf bank_mask:0xf bound_ctrl:1
	v_add_f32_dpp v124, v124, v124 quad_perm:[1,0,3,2] row_mask:0xf bank_mask:0xf bound_ctrl:1
	v_pk_mul_f32 v[140:141], v[14:15], v[32:33]
	v_pk_mul_f32 v[152:153], v[6:7], v[32:33]
	v_add_f32_dpp v122, v122, v122 quad_perm:[1,0,3,2] row_mask:0xf bank_mask:0xf bound_ctrl:1
	v_add_f32_dpp v126, v126, v126 quad_perm:[1,0,3,2] row_mask:0xf bank_mask:0xf bound_ctrl:1
	v_pk_mul_f32 v[142:143], v[16:17], v[34:35]
	v_pk_mul_f32 v[154:155], v[8:9], v[34:35]
	v_add_f32_dpp v120, v120, v120 quad_perm:[2,3,0,1] row_mask:0xf bank_mask:0xf bound_ctrl:1
	v_add_f32_dpp v124, v124, v124 quad_perm:[2,3,0,1] row_mask:0xf bank_mask:0xf bound_ctrl:1
	v_pk_fma_f32 v[136:137], v[52:53], v[68:69], v[136:137] op_sel_hi:[1,0,1]
	v_pk_fma_f32 v[148:149], v[52:53], v[68:69], v[148:149] op_sel:[0,1,0] op_sel_hi:[1,1,1]
	v_add_f32_dpp v122, v122, v122 quad_perm:[2,3,0,1] row_mask:0xf bank_mask:0xf bound_ctrl:1
	v_add_f32_dpp v126, v126, v126 quad_perm:[2,3,0,1] row_mask:0xf bank_mask:0xf bound_ctrl:1
	v_pk_fma_f32 v[138:139], v[54:55], v[68:69], v[138:139] op_sel_hi:[1,0,1]
	v_pk_fma_f32 v[150:151], v[54:55], v[68:69], v[150:151] op_sel:[0,1,0] op_sel_hi:[1,1,1]
	v_add_f32_dpp v120, v120, v120 row_half_mirror row_mask:0xf bank_mask:0xf bound_ctrl:1
	v_add_f32_dpp v124, v124, v124 row_half_mirror row_mask:0xf bank_mask:0xf bound_ctrl:1
	v_pk_fma_f32 v[140:141], v[56:57], v[68:69], v[140:141] op_sel_hi:[1,0,1]
	v_pk_fma_f32 v[152:153], v[56:57], v[68:69], v[152:153] op_sel:[0,1,0] op_sel_hi:[1,1,1]
	v_add_f32_dpp v122, v122, v122 row_half_mirror row_mask:0xf bank_mask:0xf bound_ctrl:1
	v_add_f32_dpp v126, v126, v126 row_half_mirror row_mask:0xf bank_mask:0xf bound_ctrl:1
	v_pk_fma_f32 v[142:143], v[58:59], v[68:69], v[142:143] op_sel_hi:[1,0,1]
	v_pk_fma_f32 v[154:155], v[58:59], v[68:69], v[154:155] op_sel:[0,1,0] op_sel_hi:[1,1,1]
	v_mul_f32_e32 v144, v68, v71
	v_mul_f32_e32 v145, v69, v71
	v_pk_fma_f32 v[10:11], v[44:45], v[120:121], v[136:137] op_sel_hi:[1,0,1] neg_lo:[0,1,0] neg_hi:[0,1,0]
	v_pk_fma_f32 v[2:3], v[44:45], v[124:125], v[148:149] op_sel_hi:[1,0,1] neg_lo:[0,1,0] neg_hi:[0,1,0]
	v_fma_f32 v144, -v120, v70, v144
	v_fma_f32 v145, -v124, v70, v145
	v_pk_fma_f32 v[12:13], v[46:47], v[120:121], v[138:139] op_sel_hi:[1,0,1] neg_lo:[0,1,0] neg_hi:[0,1,0]
	v_pk_fma_f32 v[4:5], v[46:47], v[124:125], v[150:151] op_sel_hi:[1,0,1] neg_lo:[0,1,0] neg_hi:[0,1,0]
	v_add_f32_e32 v128, v122, v144
	v_add_f32_e32 v129, v126, v145
	v_pk_fma_f32 v[14:15], v[48:49], v[120:121], v[140:141] op_sel_hi:[1,0,1] neg_lo:[0,1,0] neg_hi:[0,1,0]
	v_pk_fma_f32 v[6:7], v[48:49], v[124:125], v[152:153] op_sel_hi:[1,0,1] neg_lo:[0,1,0] neg_hi:[0,1,0]
	ds_write_b32 v156, v128 offset:512
	ds_write_b32 v157, v129 offset:512
	v_pk_fma_f32 v[16:17], v[50:51], v[120:121], v[142:143] op_sel_hi:[1,0,1] neg_lo:[0,1,0] neg_hi:[0,1,0]
	v_pk_fma_f32 v[8:9], v[50:51], v[124:125], v[154:155] op_sel_hi:[1,0,1] neg_lo:[0,1,0] neg_hi:[0,1,0]
	ds_read_b128 v[28:31], v130 offset:6208
	ds_read_b128 v[32:35], v130 offset:6224
	ds_read_b128 v[36:39], v130 offset:6464
	ds_read_b128 v[40:43], v130 offset:6480
	ds_read_b128 v[44:47], v130 offset:6720
	ds_read_b128 v[48:51], v130 offset:6736
	ds_read_b128 v[52:55], v130 offset:6976
	ds_read_b128 v[56:59], v130 offset:6992
	ds_read_b128 v[60:63], v130 offset:7232
	ds_read_b128 v[64:67], v130 offset:7248
	ds_read_b32 v68, v132 offset:6208
	ds_read_b32 v69, v132 offset:6240
	ds_read_b64 v[70:71], v133 offset:7744
	s_waitcnt lgkmcnt(13)
; #define LAS __attribute__((address_space(3)))
; template <int R>
; __device__ __forceinline__ void rw_task(const Params& p, LAS unsigned char* shm, const int tid, const int s, const int d, const int h, const int half) {
;     ...
;                     { const f32x4 a = *(const LAS f32x4*)(sb + 8 * j), b = *(const LAS f32x4*)(sb + 8 * j + 4); ww[0] = (f32x2){a[0], a[1]}; ww[1] = (f32x2){a[2], a[3]}; ww[2] = (f32x2){b[0], b[1]}; ww[3] = (f32x2){b[2], b[3]}; }
;                     { const f32x4 a = *(const LAS f32x4*)(sb + 64 + 8 * j), b = *(const LAS f32x4*)(sb + 64 + 8 * j + 4); kk[0] = (f32x2){a[0], a[1]}; kk[1] = (f32x2){a[2], a[3]}; kk[2] = (f32x2){b[0], b[1]}; kk[3] = (f32x2){b[2], b[3]}; }
;                     { const f32x4 a = *(const LAS f32x4*)(sb + 128 + 8 * j), b = *(const LAS f32x4*)(sb + 128 + 8 * j + 4); bb[0] = (f32x2){a[0], a[1]}; bb[1] = (f32x2){a[2], a[3]}; bb[2] = (f32x2){b[0], b[1]}; bb[3] = (f32x2){b[2], b[3]}; }
;                     { const f32x4 a = *(const LAS f32x4*)(sb + 192 + 8 * j), b = *(const LAS f32x4*)(sb + 192 + 8 * j + 4); kc[0] = (f32x2){a[0], a[1]}; kc[1] = (f32x2){a[2], a[3]}; kc[2] = (f32x2){b[0], b[1]}; kc[3] = (f32x2){b[2], b[3]}; }
;                     { const f32x4 a = *(const LAS f32x4*)(sb + 256 + 8 * j), b = *(const LAS f32x4*)(sb + 256 + 8 * j + 4); wr[0] = (f32x2){a[0], a[1]}; wr[1] = (f32x2){a[2], a[3]}; wr[2] = (f32x2){b[0], b[1]}; wr[3] = (f32x2){b[2], b[3]}; }
;                     const float v0 = sb[320 + row0], v1 = R == 2 ? sb[320 + row1] : 0.f; const f32x2 sc = *(const LAS f32x2*)(sb + 384); const float br = sc[0], kr = sc[1];
;                     if constexpr (R == 2) {
;                     f32x2 pa0 = s0[0] * kk[0], px0 = s0[0] * wr[0], pa1 = s1[0] * kk[0], px1 = s1[0] * wr[0];
; #pragma unroll
;                     for (int e = 1; e < 4; ++e) { pa0 += s0[e] * kk[e]; px0 += s0[e] * wr[e]; pa1 += s1[e] * kk[e]; px1 += s1[e] * wr[e]; }
;                     const float sa0 = red8(pa0[0] + pa0[1]), x0 = red8(px0[0] + px0[1]), sa1 = red8(pa1[0] + pa1[1]), x1 = red8(px1[0] + px1[1]);
;                     const float o0 = x0 - sa0 * br + v0 * kr, o1 = x1 - sa1 * br + v1 * kr;
;                     const f32x2 nsa0 = (f32x2){-sa0, -sa0}, nsa1 = (f32x2){-sa1, -sa1}, vv0 = (f32x2){v0, v0}, vv1 = (f32x2){v1, v1};
; #pragma unroll
	v_pk_mul_f32 v[120:121], v[10:11], v[82:83]
	v_pk_mul_f32 v[124:125], v[2:3], v[82:83]
	v_pk_mul_f32 v[122:123], v[10:11], v[108:109]
	v_pk_mul_f32 v[126:127], v[2:3], v[108:109]
	v_pk_fma_f32 v[120:121], v[12:13], v[84:85], v[120:121]
	v_pk_fma_f32 v[124:125], v[4:5], v[84:85], v[124:125]
	v_pk_fma_f32 v[122:123], v[12:13], v[110:111], v[122:123]
	v_pk_fma_f32 v[126:127], v[4:5], v[110:111], v[126:127]
	v_pk_fma_f32 v[120:121], v[14:15], v[86:87], v[120:121]
	v_pk_fma_f32 v[124:125], v[6:7], v[86:87], v[124:125]
	v_pk_fma_f32 v[122:123], v[14:15], v[112:113], v[122:123]
	v_pk_fma_f32 v[126:127], v[6:7], v[112:113], v[126:127]
	v_pk_fma_f32 v[120:121], v[16:17], v[88:89], v[120:121]
	v_pk_fma_f32 v[124:125], v[8:9], v[88:89], v[124:125]
	v_pk_fma_f32 v[122:123], v[16:17], v[114:115], v[122:123]
	v_pk_fma_f32 v[126:127], v[8:9], v[114:115], v[126:127]
	v_pk_mul_f32 v[136:137], v[10:11], v[74:75]
	v_pk_mul_f32 v[148:149], v[2:3], v[74:75]
	v_add_f32_e32 v120, v120, v121
	v_add_f32_e32 v124, v124, v125
	v_add_f32_e32 v122, v122, v123
	v_add_f32_e32 v126, v126, v127
	v_pk_mul_f32 v[138:139], v[12:13], v[76:77]
	v_pk_mul_f32 v[150:151], v[4:5], v[76:77]
	v_add_f32_dpp v120, v120, v120 quad_perm:[1,0,3,2] row_mask:0xf bank_mask:0xf bound_ctrl:1
	v_add_f32_dpp v124, v124, v124 quad_perm:[1,0,3,2] row_mask:0xf bank_mask:0xf bound_ctrl:1
	v_pk_mul_f32 v[140:141], v[14:15], v[78:79]
	v_pk_mul_f32 v[152:153], v[6:7], v[78:79]
	v_add_f32_dpp v122, v122, v122 quad_perm:[1,0,3,2] row_mask:0xf bank_mask:0xf bound_ctrl:1
	v_add_f32_dpp v126, v126, v126 quad_perm:[1,0,3,2] row_mask:0xf bank_mask:0xf bound_ctrl:1
	v_pk_mul_f32 v[142:143], v[16:17], v[80:81]
	v_pk_mul_f32 v[154:155], v[8:9], v[80:81]
	v_add_f32_dpp v120, v120, v120 quad_perm:[2,3,0,1] row_mask:0xf bank_mask:0xf bound_ctrl:1
	v_add_f32_dpp v124, v124, v124 quad_perm:[2,3,0,1] row_mask:0xf bank_mask:0xf bound_ctrl:1
	v_pk_fma_f32 v[136:137], v[100:101], v[116:117], v[136:137] op_sel_hi:[1,0,1]
	v_pk_fma_f32 v[148:149], v[100:101], v[116:117], v[148:149] op_sel:[0,1,0] op_sel_hi:[1,1,1]
	v_add_f32_dpp v122, v122, v122 quad_perm:[2,3,0,1] row_mask:0xf bank_mask:0xf bound_ctrl:1
	v_add_f32_dpp v126, v126, v126 quad_perm:[2,3,0,1] row_mask:0xf bank_mask:0xf bound_ctrl:1
	v_pk_fma_f32 v[138:139], v[102:103], v[116:117], v[138:139] op_sel_hi:[1,0,1]
	v_pk_fma_f32 v[150:151], v[102:103], v[116:117], v[150:151] op_sel:[0,1,0] op_sel_hi:[1,1,1]
	v_add_f32_dpp v120, v120, v120 row_half_mirror row_mask:0xf bank_mask:0xf bound_ctrl:1
	v_add_f32_dpp v124, v124, v124 row_half_mirror row_mask:0xf bank_mask:0xf bound_ctrl:1
	v_pk_fma_f32 v[140:141], v[104:105], v[116:117], v[140:141] op_sel_hi:[1,0,1]
	v_pk_fma_f32 v[152:153], v[104:105], v[116:117], v[152:153] op_sel:[0,1,0] op_sel_hi:[1,1,1]
	v_add_f32_dpp v122, v122, v122 row_half_mirror row_mask:0xf bank_mask:0xf bound_ctrl:1
	v_add_f32_dpp v126, v126, v126 row_half_mirror row_mask:0xf bank_mask:0xf bound_ctrl:1
	v_pk_fma_f32 v[142:143], v[106:107], v[116:117], v[142:143] op_sel_hi:[1,0,1]
	v_pk_fma_f32 v[154:155], v[106:107], v[116:117], v[154:155] op_sel:[0,1,0] op_sel_hi:[1,1,1]
	v_mul_f32_e32 v144, v116, v119
	v_mul_f32_e32 v145, v117, v119
	v_pk_fma_f32 v[10:11], v[92:93], v[120:121], v[136:137] op_sel_hi:[1,0,1] neg_lo:[0,1,0] neg_hi:[0,1,0]
	v_pk_fma_f32 v[2:3], v[92:93], v[124:125], v[148:149] op_sel_hi:[1,0,1] neg_lo:[0,1,0] neg_hi:[0,1,0]
	v_fma_f32 v144, -v120, v118, v144
	v_fma_f32 v145, -v124, v118, v145
	v_pk_fma_f32 v[12:13], v[94:95], v[120:121], v[138:139] op_sel_hi:[1,0,1] neg_lo:[0,1,0] neg_hi:[0,1,0]
	v_pk_fma_f32 v[4:5], v[94:95], v[124:125], v[150:151] op_sel_hi:[1,0,1] neg_lo:[0,1,0] neg_hi:[0,1,0]
	v_add_f32_e32 v128, v122, v144
	v_add_f32_e32 v129, v126, v145
	v_pk_fma_f32 v[14:15], v[96:97], v[120:121], v[140:141] op_sel_hi:[1,0,1] neg_lo:[0,1,0] neg_hi:[0,1,0]
	v_pk_fma_f32 v[6:7], v[96:97], v[124:125], v[152:153] op_sel_hi:[1,0,1] neg_lo:[0,1,0] neg_hi:[0,1,0]
	ds_write_b32 v156, v128 offset:768
	ds_write_b32 v157, v129 offset:768
	v_pk_fma_f32 v[16:17], v[98:99], v[120:121], v[142:143] op_sel_hi:[1,0,1] neg_lo:[0,1,0] neg_hi:[0,1,0]
	v_pk_fma_f32 v[8:9], v[98:99], v[124:125], v[154:155] op_sel_hi:[1,0,1] neg_lo:[0,1,0] neg_hi:[0,1,0]
	ds_read_b128 v[74:77], v130 offset:7760
	ds_read_b128 v[78:81], v130 offset:7776
	ds_read_b128 v[82:85], v130 offset:8016
	ds_read_b128 v[86:89], v130 offset:8032
	ds_read_b128 v[92:95], v130 offset:8272
	ds_read_b128 v[96:99], v130 offset:8288
	ds_read_b128 v[100:103], v130 offset:8528
	ds_read_b128 v[104:107], v130 offset:8544
	ds_read_b128 v[108:111], v130 offset:8784
	ds_read_b128 v[112:115], v130 offset:8800
	ds_read_b32 v116, v132 offset:7760
	ds_read_b32 v117, v132 offset:7792
	ds_read_b64 v[118:119], v133 offset:9296
	s_waitcnt lgkmcnt(13)
; #define LAS __attribute__((address_space(3)))
; template <int R>
; __device__ __forceinline__ void rw_task(const Params& p, LAS unsigned char* shm, const int tid, const int s, const int d, const int h, const int half) {
;     ...
;                     { const f32x4 a = *(const LAS f32x4*)(sb + 8 * j), b = *(const LAS f32x4*)(sb + 8 * j + 4); ww[0] = (f32x2){a[0], a[1]}; ww[1] = (f32x2){a[2], a[3]}; ww[2] = (f32x2){b[0], b[1]}; ww[3] = (f32x2){b[2], b[3]}; }
;                     { const f32x4 a = *(const LAS f32x4*)(sb + 64 + 8 * j), b = *(const LAS f32x4*)(sb + 64 + 8 * j + 4); kk[0] = (f32x2){a[0], a[1]}; kk[1] = (f32x2){a[2], a[3]}; kk[2] = (f32x2){b[0], b[1]}; kk[3] = (f32x2){b[2], b[3]}; }
;                     { const f32x4 a = *(const LAS f32x4*)(sb + 128 + 8 * j), b = *(const LAS f32x4*)(sb + 128 + 8 * j + 4); bb[0] = (f32x2){a[0], a[1]}; bb[1] = (f32x2){a[2], a[3]}; bb[2] = (f32x2){b[0], b[1]}; bb[3] = (f32x2){b[2], b[3]}; }
;                     { const f32x4 a = *(const LAS f32x4*)(sb + 192 + 8 * j), b = *(const LAS f32x4*)(sb + 192 + 8 * j + 4); kc[0] = (f32x2){a[0], a[1]}; kc[1] = (f32x2){a[2], a[3]}; kc[2] = (f32x2){b[0], b[1]}; kc[3] = (f32x2){b[2], b[3]}; }
;                     { const f32x4 a = *(const LAS f32x4*)(sb + 256 + 8 * j), b = *(const LAS f32x4*)(sb + 256 + 8 * j + 4); wr[0] = (f32x2){a[0], a[1]}; wr[1] = (f32x2){a[2], a[3]}; wr[2] = (f32x2){b[0], b[1]}; wr[3] = (f32x2){b[2], b[3]}; }
;                     const float v0 = sb[320 + row0], v1 = R == 2 ? sb[320 + row1] : 0.f; const f32x2 sc = *(const LAS f32x2*)(sb + 384); const float br = sc[0], kr = sc[1];
;                     if constexpr (R == 2) {
;                     f32x2 pa0 = s0[0] * kk[0], px0 = s0[0] * wr[0], pa1 = s1[0] * kk[0], px1 = s1[0] * wr[0];
; #pragma unroll
;                     for (int e = 1; e < 4; ++e) { pa0 += s0[e] * kk[e]; px0 += s0[e] * wr[e]; pa1 += s1[e] * kk[e]; px1 += s1[e] * wr[e]; }
;                     const float sa0 = red8(pa0[0] + pa0[1]), x0 = red8(px0[0] + px0[1]), sa1 = red8(pa1[0] + pa1[1]), x1 = red8(px1[0] + px1[1]);
;                     const float o0 = x0 - sa0 * br + v0 * kr, o1 = x1 - sa1 * br + v1 * kr;
;                     const f32x2 nsa0 = (f32x2){-sa0, -sa0}, nsa1 = (f32x2){-sa1, -sa1}, vv0 = (f32x2){v0, v0}, vv1 = (f32x2){v1, v1};
; #pragma unroll
	v_pk_mul_f32 v[120:121], v[10:11], v[36:37]
	v_pk_mul_f32 v[124:125], v[2:3], v[36:37]
	v_pk_mul_f32 v[122:123], v[10:11], v[60:61]
	v_pk_mul_f32 v[126:127], v[2:3], v[60:61]
	v_pk_fma_f32 v[120:121], v[12:13], v[38:39], v[120:121]
	v_pk_fma_f32 v[124:125], v[4:5], v[38:39], v[124:125]
	v_pk_fma_f32 v[122:123], v[12:13], v[62:63], v[122:123]
	v_pk_fma_f32 v[126:127], v[4:5], v[62:63], v[126:127]
	v_pk_fma_f32 v[120:121], v[14:15], v[40:41], v[120:121]
	v_pk_fma_f32 v[124:125], v[6:7], v[40:41], v[124:125]
	v_pk_fma_f32 v[122:123], v[14:15], v[64:65], v[122:123]
	v_pk_fma_f32 v[126:127], v[6:7], v[64:65], v[126:127]
	v_pk_fma_f32 v[120:121], v[16:17], v[42:43], v[120:121]
	v_pk_fma_f32 v[124:125], v[8:9], v[42:43], v[124:125]
	v_pk_fma_f32 v[122:123], v[16:17], v[66:67], v[122:123]
	v_pk_fma_f32 v[126:127], v[8:9], v[66:67], v[126:127]
	v_pk_mul_f32 v[136:137], v[10:11], v[28:29]
	v_pk_mul_f32 v[148:149], v[2:3], v[28:29]
	v_add_f32_e32 v120, v120, v121
	v_add_f32_e32 v124, v124, v125
	v_add_f32_e32 v122, v122, v123
	v_add_f32_e32 v126, v126, v127
	v_pk_mul_f32 v[138:139], v[12:13], v[30:31]
	v_pk_mul_f32 v[150:151], v[4:5], v[30:31]
	v_add_f32_dpp v120, v120, v120 quad_perm:[1,0,3,2] row_mask:0xf bank_mask:0xf bound_ctrl:1
	v_add_f32_dpp v124, v124, v124 quad_perm:[1,0,3,2] row_mask:0xf bank_mask:0xf bound_ctrl:1
	v_pk_mul_f32 v[140:141], v[14:15], v[32:33]
	v_pk_mul_f32 v[152:153], v[6:7], v[32:33]
	v_add_f32_dpp v122, v122, v122 quad_perm:[1,0,3,2] row_mask:0xf bank_mask:0xf bound_ctrl:1
	v_add_f32_dpp v126, v126, v126 quad_perm:[1,0,3,2] row_mask:0xf bank_mask:0xf bound_ctrl:1
	v_pk_mul_f32 v[142:143], v[16:17], v[34:35]
	v_pk_mul_f32 v[154:155], v[8:9], v[34:35]
	v_add_f32_dpp v120, v120, v120 quad_perm:[2,3,0,1] row_mask:0xf bank_mask:0xf bound_ctrl:1
	v_add_f32_dpp v124, v124, v124 quad_perm:[2,3,0,1] row_mask:0xf bank_mask:0xf bound_ctrl:1
	v_pk_fma_f32 v[136:137], v[52:53], v[68:69], v[136:137] op_sel_hi:[1,0,1]
	v_pk_fma_f32 v[148:149], v[52:53], v[68:69], v[148:149] op_sel:[0,1,0] op_sel_hi:[1,1,1]
	v_add_f32_dpp v122, v122, v122 quad_perm:[2,3,0,1] row_mask:0xf bank_mask:0xf bound_ctrl:1
	v_add_f32_dpp v126, v126, v126 quad_perm:[2,3,0,1] row_mask:0xf bank_mask:0xf bound_ctrl:1
	v_pk_fma_f32 v[138:139], v[54:55], v[68:69], v[138:139] op_sel_hi:[1,0,1]
	v_pk_fma_f32 v[150:151], v[54:55], v[68:69], v[150:151] op_sel:[0,1,0] op_sel_hi:[1,1,1]
	v_add_f32_dpp v120, v120, v120 row_half_mirror row_mask:0xf bank_mask:0xf bound_ctrl:1
	v_add_f32_dpp v124, v124, v124 row_half_mirror row_mask:0xf bank_mask:0xf bound_ctrl:1
	v_pk_fma_f32 v[140:141], v[56:57], v[68:69], v[140:141] op_sel_hi:[1,0,1]
	v_pk_fma_f32 v[152:153], v[56:57], v[68:69], v[152:153] op_sel:[0,1,0] op_sel_hi:[1,1,1]
	v_add_f32_dpp v122, v122, v122 row_half_mirror row_mask:0xf bank_mask:0xf bound_ctrl:1
	v_add_f32_dpp v126, v126, v126 row_half_mirror row_mask:0xf bank_mask:0xf bound_ctrl:1
	v_pk_fma_f32 v[142:143], v[58:59], v[68:69], v[142:143] op_sel_hi:[1,0,1]
	v_pk_fma_f32 v[154:155], v[58:59], v[68:69], v[154:155] op_sel:[0,1,0] op_sel_hi:[1,1,1]
	v_mul_f32_e32 v144, v68, v71
	v_mul_f32_e32 v145, v69, v71
	v_pk_fma_f32 v[10:11], v[44:45], v[120:121], v[136:137] op_sel_hi:[1,0,1] neg_lo:[0,1,0] neg_hi:[0,1,0]
	v_pk_fma_f32 v[2:3], v[44:45], v[124:125], v[148:149] op_sel_hi:[1,0,1] neg_lo:[0,1,0] neg_hi:[0,1,0]
	v_fma_f32 v144, -v120, v70, v144
	v_fma_f32 v145, -v124, v70, v145
	v_pk_fma_f32 v[12:13], v[46:47], v[120:121], v[138:139] op_sel_hi:[1,0,1] neg_lo:[0,1,0] neg_hi:[0,1,0]
	v_pk_fma_f32 v[4:5], v[46:47], v[124:125], v[150:151] op_sel_hi:[1,0,1] neg_lo:[0,1,0] neg_hi:[0,1,0]
	v_add_f32_e32 v128, v122, v144
	v_add_f32_e32 v129, v126, v145
	v_pk_fma_f32 v[14:15], v[48:49], v[120:121], v[140:141] op_sel_hi:[1,0,1] neg_lo:[0,1,0] neg_hi:[0,1,0]
	v_pk_fma_f32 v[6:7], v[48:49], v[124:125], v[152:153] op_sel_hi:[1,0,1] neg_lo:[0,1,0] neg_hi:[0,1,0]
	ds_write_b32 v156, v128 offset:1024
	ds_write_b32 v157, v129 offset:1024
	v_pk_fma_f32 v[16:17], v[50:51], v[120:121], v[142:143] op_sel_hi:[1,0,1] neg_lo:[0,1,0] neg_hi:[0,1,0]
	v_pk_fma_f32 v[8:9], v[50:51], v[124:125], v[154:155] op_sel_hi:[1,0,1] neg_lo:[0,1,0] neg_hi:[0,1,0]
	ds_read_b128 v[28:31], v130 offset:9312
	ds_read_b128 v[32:35], v130 offset:9328
	ds_read_b128 v[36:39], v130 offset:9568
	ds_read_b128 v[40:43], v130 offset:9584
	ds_read_b128 v[44:47], v130 offset:9824
	ds_read_b128 v[48:51], v130 offset:9840
	ds_read_b128 v[52:55], v130 offset:10080
	ds_read_b128 v[56:59], v130 offset:10096
	ds_read_b128 v[60:63], v130 offset:10336
	ds_read_b128 v[64:67], v130 offset:10352
	ds_read_b32 v68, v132 offset:9312
	ds_read_b32 v69, v132 offset:9344
	ds_read_b64 v[70:71], v133 offset:10848
	s_waitcnt lgkmcnt(13)
; #define LAS __attribute__((address_space(3)))
; template <int R>
; __device__ __forceinline__ void rw_task(const Params& p, LAS unsigned char* shm, const int tid, const int s, const int d, const int h, const int half) {
;     ...
;                     { const f32x4 a = *(const LAS f32x4*)(sb + 8 * j), b = *(const LAS f32x4*)(sb + 8 * j + 4); ww[0] = (f32x2){a[0], a[1]}; ww[1] = (f32x2){a[2], a[3]}; ww[2] = (f32x2){b[0], b[1]}; ww[3] = (f32x2){b[2], b[3]}; }
;                     { const f32x4 a = *(const LAS f32x4*)(sb + 64 + 8 * j), b = *(const LAS f32x4*)(sb + 64 + 8 * j + 4); kk[0] = (f32x2){a[0], a[1]}; kk[1] = (f32x2){a[2], a[3]}; kk[2] = (f32x2){b[0], b[1]}; kk[3] = (f32x2){b[2], b[3]}; }
;                     { const f32x4 a = *(const LAS f32x4*)(sb + 128 + 8 * j), b = *(const LAS f32x4*)(sb + 128 + 8 * j + 4); bb[0] = (f32x2){a[0], a[1]}; bb[1] = (f32x2){a[2], a[3]}; bb[2] = (f32x2){b[0], b[1]}; bb[3] = (f32x2){b[2], b[3]}; }
;                     { const f32x4 a = *(const LAS f32x4*)(sb + 192 + 8 * j), b = *(const LAS f32x4*)(sb + 192 + 8 * j + 4); kc[0] = (f32x2){a[0], a[1]}; kc[1] = (f32x2){a[2], a[3]}; kc[2] = (f32x2){b[0], b[1]}; kc[3] = (f32x2){b[2], b[3]}; }
;                     { const f32x4 a = *(const LAS f32x4*)(sb + 256 + 8 * j), b = *(const LAS f32x4*)(sb + 256 + 8 * j + 4); wr[0] = (f32x2){a[0], a[1]}; wr[1] = (f32x2){a[2], a[3]}; wr[2] = (f32x2){b[0], b[1]}; wr[3] = (f32x2){b[2], b[3]}; }
;                     const float v0 = sb[320 + row0], v1 = R == 2 ? sb[320 + row1] : 0.f; const f32x2 sc = *(const LAS f32x2*)(sb + 384); const float br = sc[0], kr = sc[1];
;                     if constexpr (R == 2) {
;                     f32x2 pa0 = s0[0] * kk[0], px0 = s0[0] * wr[0], pa1 = s1[0] * kk[0], px1 = s1[0] * wr[0];
; #pragma unroll
;                     for (int e = 1; e < 4; ++e) { pa0 += s0[e] * kk[e]; px0 += s0[e] * wr[e]; pa1 += s1[e] * kk[e]; px1 += s1[e] * wr[e]; }
;                     const float sa0 = red8(pa0[0] + pa0[1]), x0 = red8(px0[0] + px0[1]), sa1 = red8(pa1[0] + pa1[1]), x1 = red8(px1[0] + px1[1]);
;                     const float o0 = x0 - sa0 * br + v0 * kr, o1 = x1 - sa1 * br + v1 * kr;
;                     const f32x2 nsa0 = (f32x2){-sa0, -sa0}, nsa1 = (f32x2){-sa1, -sa1}, vv0 = (f32x2){v0, v0}, vv1 = (f32x2){v1, v1};
; #pragma unroll
	v_pk_mul_f32 v[120:121], v[10:11], v[82:83]
	v_pk_mul_f32 v[124:125], v[2:3], v[82:83]
	v_pk_mul_f32 v[122:123], v[10:11], v[108:109]
	v_pk_mul_f32 v[126:127], v[2:3], v[108:109]
	v_pk_fma_f32 v[120:121], v[12:13], v[84:85], v[120:121]
	v_pk_fma_f32 v[124:125], v[4:5], v[84:85], v[124:125]
	v_pk_fma_f32 v[122:123], v[12:13], v[110:111], v[122:123]
	v_pk_fma_f32 v[126:127], v[4:5], v[110:111], v[126:127]
	v_pk_fma_f32 v[120:121], v[14:15], v[86:87], v[120:121]
	v_pk_fma_f32 v[124:125], v[6:7], v[86:87], v[124:125]
	v_pk_fma_f32 v[122:123], v[14:15], v[112:113], v[122:123]
	v_pk_fma_f32 v[126:127], v[6:7], v[112:113], v[126:127]
	v_pk_fma_f32 v[120:121], v[16:17], v[88:89], v[120:121]
	v_pk_fma_f32 v[124:125], v[8:9], v[88:89], v[124:125]
	v_pk_fma_f32 v[122:123], v[16:17], v[114:115], v[122:123]
	v_pk_fma_f32 v[126:127], v[8:9], v[114:115], v[126:127]
	v_pk_mul_f32 v[136:137], v[10:11], v[74:75]
	v_pk_mul_f32 v[148:149], v[2:3], v[74:75]
	v_add_f32_e32 v120, v120, v121
	v_add_f32_e32 v124, v124, v125
	v_add_f32_e32 v122, v122, v123
	v_add_f32_e32 v126, v126, v127
	v_pk_mul_f32 v[138:139], v[12:13], v[76:77]
	v_pk_mul_f32 v[150:151], v[4:5], v[76:77]
	v_add_f32_dpp v120, v120, v120 quad_perm:[1,0,3,2] row_mask:0xf bank_mask:0xf bound_ctrl:1
	v_add_f32_dpp v124, v124, v124 quad_perm:[1,0,3,2] row_mask:0xf bank_mask:0xf bound_ctrl:1
	v_pk_mul_f32 v[140:141], v[14:15], v[78:79]
	v_pk_mul_f32 v[152:153], v[6:7], v[78:79]
	v_add_f32_dpp v122, v122, v122 quad_perm:[1,0,3,2] row_mask:0xf bank_mask:0xf bound_ctrl:1
	v_add_f32_dpp v126, v126, v126 quad_perm:[1,0,3,2] row_mask:0xf bank_mask:0xf bound_ctrl:1
	v_pk_mul_f32 v[142:143], v[16:17], v[80:81]
	v_pk_mul_f32 v[154:155], v[8:9], v[80:81]
	v_add_f32_dpp v120, v120, v120 quad_perm:[2,3,0,1] row_mask:0xf bank_mask:0xf bound_ctrl:1
	v_add_f32_dpp v124, v124, v124 quad_perm:[2,3,0,1] row_mask:0xf bank_mask:0xf bound_ctrl:1
	v_pk_fma_f32 v[136:137], v[100:101], v[116:117], v[136:137] op_sel_hi:[1,0,1]
	v_pk_fma_f32 v[148:149], v[100:101], v[116:117], v[148:149] op_sel:[0,1,0] op_sel_hi:[1,1,1]
	v_add_f32_dpp v122, v122, v122 quad_perm:[2,3,0,1] row_mask:0xf bank_mask:0xf bound_ctrl:1
	v_add_f32_dpp v126, v126, v126 quad_perm:[2,3,0,1] row_mask:0xf bank_mask:0xf bound_ctrl:1
	v_pk_fma_f32 v[138:139], v[102:103], v[116:117], v[138:139] op_sel_hi:[1,0,1]
	v_pk_fma_f32 v[150:151], v[102:103], v[116:117], v[150:151] op_sel:[0,1,0] op_sel_hi:[1,1,1]
	v_add_f32_dpp v120, v120, v120 row_half_mirror row_mask:0xf bank_mask:0xf bound_ctrl:1
	v_add_f32_dpp v124, v124, v124 row_half_mirror row_mask:0xf bank_mask:0xf bound_ctrl:1
	v_pk_fma_f32 v[140:141], v[104:105], v[116:117], v[140:141] op_sel_hi:[1,0,1]
	v_pk_fma_f32 v[152:153], v[104:105], v[116:117], v[152:153] op_sel:[0,1,0] op_sel_hi:[1,1,1]
	v_add_f32_dpp v122, v122, v122 row_half_mirror row_mask:0xf bank_mask:0xf bound_ctrl:1
	v_add_f32_dpp v126, v126, v126 row_half_mirror row_mask:0xf bank_mask:0xf bound_ctrl:1
	v_pk_fma_f32 v[142:143], v[106:107], v[116:117], v[142:143] op_sel_hi:[1,0,1]
	v_pk_fma_f32 v[154:155], v[106:107], v[116:117], v[154:155] op_sel:[0,1,0] op_sel_hi:[1,1,1]
	v_mul_f32_e32 v144, v116, v119
	v_mul_f32_e32 v145, v117, v119
	v_pk_fma_f32 v[10:11], v[92:93], v[120:121], v[136:137] op_sel_hi:[1,0,1] neg_lo:[0,1,0] neg_hi:[0,1,0]
	v_pk_fma_f32 v[2:3], v[92:93], v[124:125], v[148:149] op_sel_hi:[1,0,1] neg_lo:[0,1,0] neg_hi:[0,1,0]
	v_fma_f32 v144, -v120, v118, v144
	v_fma_f32 v145, -v124, v118, v145
	v_pk_fma_f32 v[12:13], v[94:95], v[120:121], v[138:139] op_sel_hi:[1,0,1] neg_lo:[0,1,0] neg_hi:[0,1,0]
	v_pk_fma_f32 v[4:5], v[94:95], v[124:125], v[150:151] op_sel_hi:[1,0,1] neg_lo:[0,1,0] neg_hi:[0,1,0]
	v_add_f32_e32 v128, v122, v144
	v_add_f32_e32 v129, v126, v145
	v_pk_fma_f32 v[14:15], v[96:97], v[120:121], v[140:141] op_sel_hi:[1,0,1] neg_lo:[0,1,0] neg_hi:[0,1,0]
	v_pk_fma_f32 v[6:7], v[96:97], v[124:125], v[152:153] op_sel_hi:[1,0,1] neg_lo:[0,1,0] neg_hi:[0,1,0]
	ds_write_b32 v156, v128 offset:1280
	ds_write_b32 v157, v129 offset:1280
	v_pk_fma_f32 v[16:17], v[98:99], v[120:121], v[142:143] op_sel_hi:[1,0,1] neg_lo:[0,1,0] neg_hi:[0,1,0]
	v_pk_fma_f32 v[8:9], v[98:99], v[124:125], v[154:155] op_sel_hi:[1,0,1] neg_lo:[0,1,0] neg_hi:[0,1,0]
	ds_read_b128 v[74:77], v130 offset:10864
	ds_read_b128 v[78:81], v130 offset:10880
	ds_read_b128 v[82:85], v130 offset:11120
	ds_read_b128 v[86:89], v130 offset:11136
	ds_read_b128 v[92:95], v130 offset:11376
	ds_read_b128 v[96:99], v130 offset:11392
	ds_read_b128 v[100:103], v130 offset:11632
	ds_read_b128 v[104:107], v130 offset:11648
	ds_read_b128 v[108:111], v130 offset:11888
	ds_read_b128 v[112:115], v130 offset:11904
	ds_read_b32 v116, v132 offset:10864
	ds_read_b32 v117, v132 offset:10896
	ds_read_b64 v[118:119], v133 offset:12400
	s_waitcnt lgkmcnt(13)
; #define LAS __attribute__((address_space(3)))
; template <int R>
; __device__ __forceinline__ void rw_task(const Params& p, LAS unsigned char* shm, const int tid, const int s, const int d, const int h, const int half) {
;     ...
;                     { const f32x4 a = *(const LAS f32x4*)(sb + 8 * j), b = *(const LAS f32x4*)(sb + 8 * j + 4); ww[0] = (f32x2){a[0], a[1]}; ww[1] = (f32x2){a[2], a[3]}; ww[2] = (f32x2){b[0], b[1]}; ww[3] = (f32x2){b[2], b[3]}; }
;                     { const f32x4 a = *(const LAS f32x4*)(sb + 64 + 8 * j), b = *(const LAS f32x4*)(sb + 64 + 8 * j + 4); kk[0] = (f32x2){a[0], a[1]}; kk[1] = (f32x2){a[2], a[3]}; kk[2] = (f32x2){b[0], b[1]}; kk[3] = (f32x2){b[2], b[3]}; }
;                     { const f32x4 a = *(const LAS f32x4*)(sb + 128 + 8 * j), b = *(const LAS f32x4*)(sb + 128 + 8 * j + 4); bb[0] = (f32x2){a[0], a[1]}; bb[1] = (f32x2){a[2], a[3]}; bb[2] = (f32x2){b[0], b[1]}; bb[3] = (f32x2){b[2], b[3]}; }
;                     { const f32x4 a = *(const LAS f32x4*)(sb + 192 + 8 * j), b = *(const LAS f32x4*)(sb + 192 + 8 * j + 4); kc[0] = (f32x2){a[0], a[1]}; kc[1] = (f32x2){a[2], a[3]}; kc[2] = (f32x2){b[0], b[1]}; kc[3] = (f32x2){b[2], b[3]}; }
;                     { const f32x4 a = *(const LAS f32x4*)(sb + 256 + 8 * j), b = *(const LAS f32x4*)(sb + 256 + 8 * j + 4); wr[0] = (f32x2){a[0], a[1]}; wr[1] = (f32x2){a[2], a[3]}; wr[2] = (f32x2){b[0], b[1]}; wr[3] = (f32x2){b[2], b[3]}; }
;                     const float v0 = sb[320 + row0], v1 = R == 2 ? sb[320 + row1] : 0.f; const f32x2 sc = *(const LAS f32x2*)(sb + 384); const float br = sc[0], kr = sc[1];
;                     if constexpr (R == 2) {
;                     f32x2 pa0 = s0[0] * kk[0], px0 = s0[0] * wr[0], pa1 = s1[0] * kk[0], px1 = s1[0] * wr[0];
; #pragma unroll
;                     for (int e = 1; e < 4; ++e) { pa0 += s0[e] * kk[e]; px0 += s0[e] * wr[e]; pa1 += s1[e] * kk[e]; px1 += s1[e] * wr[e]; }
;                     const float sa0 = red8(pa0[0] + pa0[1]), x0 = red8(px0[0] + px0[1]), sa1 = red8(pa1[0] + pa1[1]), x1 = red8(px1[0] + px1[1]);
;                     const float o0 = x0 - sa0 * br + v0 * kr, o1 = x1 - sa1 * br + v1 * kr;
;                     const f32x2 nsa0 = (f32x2){-sa0, -sa0}, nsa1 = (f32x2){-sa1, -sa1}, vv0 = (f32x2){v0, v0}, vv1 = (f32x2){v1, v1};
; #pragma unroll
	v_pk_mul_f32 v[120:121], v[10:11], v[36:37]
	v_pk_mul_f32 v[124:125], v[2:3], v[36:37]
	v_pk_mul_f32 v[122:123], v[10:11], v[60:61]
	v_pk_mul_f32 v[126:127], v[2:3], v[60:61]
	v_pk_fma_f32 v[120:121], v[12:13], v[38:39], v[120:121]
	v_pk_fma_f32 v[124:125], v[4:5], v[38:39], v[124:125]
	v_pk_fma_f32 v[122:123], v[12:13], v[62:63], v[122:123]
	v_pk_fma_f32 v[126:127], v[4:5], v[62:63], v[126:127]
	v_pk_fma_f32 v[120:121], v[14:15], v[40:41], v[120:121]
	v_pk_fma_f32 v[124:125], v[6:7], v[40:41], v[124:125]
	v_pk_fma_f32 v[122:123], v[14:15], v[64:65], v[122:123]
	v_pk_fma_f32 v[126:127], v[6:7], v[64:65], v[126:127]
	v_pk_fma_f32 v[120:121], v[16:17], v[42:43], v[120:121]
	v_pk_fma_f32 v[124:125], v[8:9], v[42:43], v[124:125]
	v_pk_fma_f32 v[122:123], v[16:17], v[66:67], v[122:123]
	v_pk_fma_f32 v[126:127], v[8:9], v[66:67], v[126:127]
	v_pk_mul_f32 v[136:137], v[10:11], v[28:29]
	v_pk_mul_f32 v[148:149], v[2:3], v[28:29]
	v_add_f32_e32 v120, v120, v121
	v_add_f32_e32 v124, v124, v125
	v_add_f32_e32 v122, v122, v123
	v_add_f32_e32 v126, v126, v127
	v_pk_mul_f32 v[138:139], v[12:13], v[30:31]
	v_pk_mul_f32 v[150:151], v[4:5], v[30:31]
	v_add_f32_dpp v120, v120, v120 quad_perm:[1,0,3,2] row_mask:0xf bank_mask:0xf bound_ctrl:1
	v_add_f32_dpp v124, v124, v124 quad_perm:[1,0,3,2] row_mask:0xf bank_mask:0xf bound_ctrl:1
	v_pk_mul_f32 v[140:141], v[14:15], v[32:33]
	v_pk_mul_f32 v[152:153], v[6:7], v[32:33]
	v_add_f32_dpp v122, v122, v122 quad_perm:[1,0,3,2] row_mask:0xf bank_mask:0xf bound_ctrl:1
	v_add_f32_dpp v126, v126, v126 quad_perm:[1,0,3,2] row_mask:0xf bank_mask:0xf bound_ctrl:1
	v_pk_mul_f32 v[142:143], v[16:17], v[34:35]
	v_pk_mul_f32 v[154:155], v[8:9], v[34:35]
	v_add_f32_dpp v120, v120, v120 quad_perm:[2,3,0,1] row_mask:0xf bank_mask:0xf bound_ctrl:1
	v_add_f32_dpp v124, v124, v124 quad_perm:[2,3,0,1] row_mask:0xf bank_mask:0xf bound_ctrl:1
	v_pk_fma_f32 v[136:137], v[52:53], v[68:69], v[136:137] op_sel_hi:[1,0,1]
	v_pk_fma_f32 v[148:149], v[52:53], v[68:69], v[148:149] op_sel:[0,1,0] op_sel_hi:[1,1,1]
	v_add_f32_dpp v122, v122, v122 quad_perm:[2,3,0,1] row_mask:0xf bank_mask:0xf bound_ctrl:1
	v_add_f32_dpp v126, v126, v126 quad_perm:[2,3,0,1] row_mask:0xf bank_mask:0xf bound_ctrl:1
	v_pk_fma_f32 v[138:139], v[54:55], v[68:69], v[138:139] op_sel_hi:[1,0,1]
	v_pk_fma_f32 v[150:151], v[54:55], v[68:69], v[150:151] op_sel:[0,1,0] op_sel_hi:[1,1,1]
	v_add_f32_dpp v120, v120, v120 row_half_mirror row_mask:0xf bank_mask:0xf bound_ctrl:1
	v_add_f32_dpp v124, v124, v124 row_half_mirror row_mask:0xf bank_mask:0xf bound_ctrl:1
	v_pk_fma_f32 v[140:141], v[56:57], v[68:69], v[140:141] op_sel_hi:[1,0,1]
	v_pk_fma_f32 v[152:153], v[56:57], v[68:69], v[152:153] op_sel:[0,1,0] op_sel_hi:[1,1,1]
	v_add_f32_dpp v122, v122, v122 row_half_mirror row_mask:0xf bank_mask:0xf bound_ctrl:1
	v_add_f32_dpp v126, v126, v126 row_half_mirror row_mask:0xf bank_mask:0xf bound_ctrl:1
	v_pk_fma_f32 v[142:143], v[58:59], v[68:69], v[142:143] op_sel_hi:[1,0,1]
	v_pk_fma_f32 v[154:155], v[58:59], v[68:69], v[154:155] op_sel:[0,1,0] op_sel_hi:[1,1,1]
	v_mul_f32_e32 v144, v68, v71
	v_mul_f32_e32 v145, v69, v71
	v_pk_fma_f32 v[10:11], v[44:45], v[120:121], v[136:137] op_sel_hi:[1,0,1] neg_lo:[0,1,0] neg_hi:[0,1,0]
	v_pk_fma_f32 v[2:3], v[44:45], v[124:125], v[148:149] op_sel_hi:[1,0,1] neg_lo:[0,1,0] neg_hi:[0,1,0]
	v_fma_f32 v144, -v120, v70, v144
	v_fma_f32 v145, -v124, v70, v145
	v_pk_fma_f32 v[12:13], v[46:47], v[120:121], v[138:139] op_sel_hi:[1,0,1] neg_lo:[0,1,0] neg_hi:[0,1,0]
	v_pk_fma_f32 v[4:5], v[46:47], v[124:125], v[150:151] op_sel_hi:[1,0,1] neg_lo:[0,1,0] neg_hi:[0,1,0]
	v_add_f32_e32 v128, v122, v144
	v_add_f32_e32 v129, v126, v145
	v_pk_fma_f32 v[14:15], v[48:49], v[120:121], v[140:141] op_sel_hi:[1,0,1] neg_lo:[0,1,0] neg_hi:[0,1,0]
	v_pk_fma_f32 v[6:7], v[48:49], v[124:125], v[152:153] op_sel_hi:[1,0,1] neg_lo:[0,1,0] neg_hi:[0,1,0]
	ds_write_b32 v156, v128 offset:1536
	ds_write_b32 v157, v129 offset:1536
	v_pk_fma_f32 v[16:17], v[50:51], v[120:121], v[142:143] op_sel_hi:[1,0,1] neg_lo:[0,1,0] neg_hi:[0,1,0]
	v_pk_fma_f32 v[8:9], v[50:51], v[124:125], v[154:155] op_sel_hi:[1,0,1] neg_lo:[0,1,0] neg_hi:[0,1,0]
	ds_read_b128 v[28:31], v130 offset:12416
	ds_read_b128 v[32:35], v130 offset:12432
	ds_read_b128 v[36:39], v130 offset:12672
	ds_read_b128 v[40:43], v130 offset:12688
	ds_read_b128 v[44:47], v130 offset:12928
	ds_read_b128 v[48:51], v130 offset:12944
	ds_read_b128 v[52:55], v130 offset:13184
	ds_read_b128 v[56:59], v130 offset:13200
	ds_read_b128 v[60:63], v130 offset:13440
	ds_read_b128 v[64:67], v130 offset:13456
	ds_read_b32 v68, v132 offset:12416
	ds_read_b32 v69, v132 offset:12448
	ds_read_b64 v[70:71], v133 offset:13952
	s_waitcnt lgkmcnt(13)
; template <int R>
; __device__ __forceinline__ void rw_task(const Params& p, LAS unsigned char* shm, const int tid, const int s, const int d, const int h, const int half) {
;     ...
;                     f32x2 pa0 = s0[0] * kk[0], px0 = s0[0] * wr[0], pa1 = s1[0] * kk[0], px1 = s1[0] * wr[0];
; #pragma unroll
;                     for (int e = 1; e < 4; ++e) { pa0 += s0[e] * kk[e]; px0 += s0[e] * wr[e]; pa1 += s1[e] * kk[e]; px1 += s1[e] * wr[e]; }
;                     const float sa0 = red8(pa0[0] + pa0[1]), x0 = red8(px0[0] + px0[1]), sa1 = red8(pa1[0] + pa1[1]), x1 = red8(px1[0] + px1[1]);
;                     const float o0 = x0 - sa0 * br + v0 * kr, o1 = x1 - sa1 * br + v1 * kr;
;                     const f32x2 nsa0 = (f32x2){-sa0, -sa0}, nsa1 = (f32x2){-sa1, -sa1}, vv0 = (f32x2){v0, v0}, vv1 = (f32x2){v1, v1};
; #pragma unroll
;                     for (int e = 0; e < 4; ++e) { s0[e] = s0[e] * ww[e] + nsa0 * bb[e] + vv0 * kc[e]; s1[e] = s1[e] * ww[e] + nsa1 * bb[e] + vv1 * kc[e]; }
;                     ow0[(st * 64) & omask] = o0; ow1[(st * 64) & omask] = o1;
;                     } else {
;                     f32x2 pa0 = s0[0] * kk[0], px0 = s0[0] * wr[0], pa1 = s0[1] * kk[1], px1 = s0[1] * wr[1];
;                     pa0 += s0[2] * kk[2]; px0 += s0[2] * wr[2]; pa1 += s0[3] * kk[3]; px1 += s0[3] * wr[3];
;                     pa0 += pa1; px0 += px1;
;                     const float sa0 = red8(pa0[0] + pa0[1]), x0 = red8(px0[0] + px0[1]);
;                     const float o0 = x0 - sa0 * br + v0 * kr;
;                     const f32x2 nsa0 = (f32x2){-sa0, -sa0}, vv0 = (f32x2){v0, v0};
; #pragma unroll
;                     for (int e = 0; e < 4; ++e) s0[e] = s0[e] * ww[e] + nsa0 * bb[e] + vv0 * kc[e];
;                     ow0[(st * 64) & omask] = o0; (void)ow1;
;                     (void)v1; (void)row1;
;                     }
;                 }
;                 __syncthreads();
	v_pk_mul_f32 v[120:121], v[10:11], v[82:83]
	v_pk_mul_f32 v[124:125], v[2:3], v[82:83]
	v_pk_mul_f32 v[122:123], v[10:11], v[108:109]
	v_pk_mul_f32 v[126:127], v[2:3], v[108:109]
	v_pk_fma_f32 v[120:121], v[12:13], v[84:85], v[120:121]
	v_pk_fma_f32 v[124:125], v[4:5], v[84:85], v[124:125]
	v_pk_fma_f32 v[122:123], v[12:13], v[110:111], v[122:123]
	v_pk_fma_f32 v[126:127], v[4:5], v[110:111], v[126:127]
	v_pk_fma_f32 v[120:121], v[14:15], v[86:87], v[120:121]
	v_pk_fma_f32 v[124:125], v[6:7], v[86:87], v[124:125]
	v_pk_fma_f32 v[122:123], v[14:15], v[112:113], v[122:123]
	v_pk_fma_f32 v[126:127], v[6:7], v[112:113], v[126:127]
	v_pk_fma_f32 v[120:121], v[16:17], v[88:89], v[120:121]
	v_pk_fma_f32 v[124:125], v[8:9], v[88:89], v[124:125]
	v_pk_fma_f32 v[122:123], v[16:17], v[114:115], v[122:123]
	v_pk_fma_f32 v[126:127], v[8:9], v[114:115], v[126:127]
	v_pk_mul_f32 v[136:137], v[10:11], v[74:75]
	v_pk_mul_f32 v[148:149], v[2:3], v[74:75]
	v_add_f32_e32 v120, v120, v121
	v_add_f32_e32 v124, v124, v125
	v_add_f32_e32 v122, v122, v123
	v_add_f32_e32 v126, v126, v127
	v_pk_mul_f32 v[138:139], v[12:13], v[76:77]
	v_pk_mul_f32 v[150:151], v[4:5], v[76:77]
	v_add_f32_dpp v120, v120, v120 quad_perm:[1,0,3,2] row_mask:0xf bank_mask:0xf bound_ctrl:1
	v_add_f32_dpp v124, v124, v124 quad_perm:[1,0,3,2] row_mask:0xf bank_mask:0xf bound_ctrl:1
	v_pk_mul_f32 v[140:141], v[14:15], v[78:79]
	v_pk_mul_f32 v[152:153], v[6:7], v[78:79]
	v_add_f32_dpp v122, v122, v122 quad_perm:[1,0,3,2] row_mask:0xf bank_mask:0xf bound_ctrl:1
	v_add_f32_dpp v126, v126, v126 quad_perm:[1,0,3,2] row_mask:0xf bank_mask:0xf bound_ctrl:1
	v_pk_mul_f32 v[142:143], v[16:17], v[80:81]
	v_pk_mul_f32 v[154:155], v[8:9], v[80:81]
	v_add_f32_dpp v120, v120, v120 quad_perm:[2,3,0,1] row_mask:0xf bank_mask:0xf bound_ctrl:1
	v_add_f32_dpp v124, v124, v124 quad_perm:[2,3,0,1] row_mask:0xf bank_mask:0xf bound_ctrl:1
	v_pk_fma_f32 v[136:137], v[100:101], v[116:117], v[136:137] op_sel_hi:[1,0,1]
	v_pk_fma_f32 v[148:149], v[100:101], v[116:117], v[148:149] op_sel:[0,1,0] op_sel_hi:[1,1,1]
	v_add_f32_dpp v122, v122, v122 quad_perm:[2,3,0,1] row_mask:0xf bank_mask:0xf bound_ctrl:1
	v_add_f32_dpp v126, v126, v126 quad_perm:[2,3,0,1] row_mask:0xf bank_mask:0xf bound_ctrl:1
	v_pk_fma_f32 v[138:139], v[102:103], v[116:117], v[138:139] op_sel_hi:[1,0,1]
	v_pk_fma_f32 v[150:151], v[102:103], v[116:117], v[150:151] op_sel:[0,1,0] op_sel_hi:[1,1,1]
	v_add_f32_dpp v120, v120, v120 row_half_mirror row_mask:0xf bank_mask:0xf bound_ctrl:1
	v_add_f32_dpp v124, v124, v124 row_half_mirror row_mask:0xf bank_mask:0xf bound_ctrl:1
	v_pk_fma_f32 v[140:141], v[104:105], v[116:117], v[140:141] op_sel_hi:[1,0,1]
	v_pk_fma_f32 v[152:153], v[104:105], v[116:117], v[152:153] op_sel:[0,1,0] op_sel_hi:[1,1,1]
	v_add_f32_dpp v122, v122, v122 row_half_mirror row_mask:0xf bank_mask:0xf bound_ctrl:1
	v_add_f32_dpp v126, v126, v126 row_half_mirror row_mask:0xf bank_mask:0xf bound_ctrl:1
	v_pk_fma_f32 v[142:143], v[106:107], v[116:117], v[142:143] op_sel_hi:[1,0,1]
	v_pk_fma_f32 v[154:155], v[106:107], v[116:117], v[154:155] op_sel:[0,1,0] op_sel_hi:[1,1,1]
	v_mul_f32_e32 v144, v116, v119
	v_mul_f32_e32 v145, v117, v119
	v_pk_fma_f32 v[10:11], v[92:93], v[120:121], v[136:137] op_sel_hi:[1,0,1] neg_lo:[0,1,0] neg_hi:[0,1,0]
	v_pk_fma_f32 v[2:3], v[92:93], v[124:125], v[148:149] op_sel_hi:[1,0,1] neg_lo:[0,1,0] neg_hi:[0,1,0]
	v_fma_f32 v144, -v120, v118, v144
	v_fma_f32 v145, -v124, v118, v145
	v_pk_fma_f32 v[12:13], v[94:95], v[120:121], v[138:139] op_sel_hi:[1,0,1] neg_lo:[0,1,0] neg_hi:[0,1,0]
	v_pk_fma_f32 v[4:5], v[94:95], v[124:125], v[150:151] op_sel_hi:[1,0,1] neg_lo:[0,1,0] neg_hi:[0,1,0]
	v_add_f32_e32 v128, v122, v144
	v_add_f32_e32 v129, v126, v145
	v_pk_fma_f32 v[14:15], v[96:97], v[120:121], v[140:141] op_sel_hi:[1,0,1] neg_lo:[0,1,0] neg_hi:[0,1,0]
	v_pk_fma_f32 v[6:7], v[96:97], v[124:125], v[152:153] op_sel_hi:[1,0,1] neg_lo:[0,1,0] neg_hi:[0,1,0]
	ds_write_b32 v156, v128 offset:1792
	ds_write_b32 v157, v129 offset:1792
	v_pk_fma_f32 v[16:17], v[98:99], v[120:121], v[142:143] op_sel_hi:[1,0,1] neg_lo:[0,1,0] neg_hi:[0,1,0]
	v_pk_fma_f32 v[8:9], v[98:99], v[124:125], v[154:155] op_sel_hi:[1,0,1] neg_lo:[0,1,0] neg_hi:[0,1,0]
	v_add_u32_e32 v130, 0x3080, v130
	v_add_u32_e32 v132, 0x3080, v132
	v_add_u32_e32 v133, 0x3080, v133
	v_add_u32_e32 v156, 0x800, v156
	v_add_u32_e32 v157, 0x800, v157
	s_add_i32 s6, s6, 1
	s_cmp_eq_u32 s6, 4
	s_cbranch_scc0 .Lrw2_step
	s_add_i32 s4, s4, 1
	s_xor_b64 s[0:1], s[0:1], -1
	s_cmpk_eq_i32 s4, 0x80
	s_waitcnt lgkmcnt(0)
	s_barrier
	s_cbranch_scc0 .LBB0_205
